# MLA attention loop: row-max/fma/exp moved into PV MFMA gaps, K-tile LDS writes hoisted, one barrier per key tile (same restructure as GQA loop)
# speedup vs baseline: 1.0435x; 1.0116x over previous
; #define SBAR() __builtin_amdgcn_sched_barrier(0)
; #define SLOAD(i, k0) do { sr_[i].vs0 = *reinterpret_cast<const bf16x8*>(vptr + (size_t)((k0) + sr) * vstr); \
;     sr_[i].vs1 = *reinterpret_cast<const bf16x8*>(vptr + (size_t)((k0) + 32 + sr) * vstr); \
;     sr_[i].ks0 = *reinterpret_cast<const bf16x8*>(kptr + (size_t)((k0) + sr) * kstr); \
;     sr_[i].ks1 = *reinterpret_cast<const bf16x8*>(kptr + (size_t)((k0) + 32 + sr) * kstr); } while (0)
; #define SWRITE(b, i) do { *(LAS bf16x8*)(V_lds + (b) * SHM_V + vst0) = sr_[i].vs0;          \
;     *(LAS bf16x8*)(V_lds + (b) * SHM_V + vst1) = sr_[i].vs1; const int kc = sc * 2;               \
;     *(LAS bf16x8*)(K_lds + (b) * SHM_K + KSWZ(sr, kc)) = sr_[i].ks0;                       \
;     *(LAS bf16x8*)(K_lds + (b) * SHM_K + KSWZ(32 + sr, kc)) = sr_[i].ks1; } while (0)
; #define SWAIT() asm volatile("s_waitcnt vmcnt(4)" ::: "memory")
; template <int NDQ, int NDV> ...
;     ...
;     SBAR(); qkt<NDQ>(pB0, pB1, K_lds + SHM_K, qr, r32, hi);
;     finishSM(pA0, pA1, alA, l_reg, pa0, pa1, pa2, pa3); SBAR();
;     SLOAD(SO, (j + 2) * 64); SBAR();
;     pv_d0<NDV>(o, vb0, pa0, pa1, pa2, pa3); partialSM(pB0, pB1, m_reg, mnB, alB, Cs, thr);
;     ...
;     __syncthreads(); SWAIT(); SWRITE(1, SO);
.LBB0_1488:
	ds_read_b128 v[32:35], v175 offset:49152
	ds_read_b128 v[36:39], v175 offset:57344
	ds_read_b128 v[192:195], v176 offset:49152
	ds_read_b128 v[196:199], v176 offset:57344
	ds_read_b128 v[200:203], v177 offset:49152
	ds_read_b128 v[204:207], v177 offset:57344
	ds_read_b128 v[208:211], v178 offset:49152
	ds_read_b128 v[212:215], v178 offset:57344
	ds_read_b128 v[216:219], v179 offset:49152
	ds_read_b128 v[220:223], v179 offset:57344
	v_add_f32_e32 v121, 0, v130
	v_add_f32_e32 v121, v134, v121
	s_waitcnt lgkmcnt(9)
	v_mfma_f32_32x32x16_bf16 v[48:63], v[32:35], v[84:87], 0
	v_add_f32_e32 v121, v131, v121
	v_add_f32_e32 v121, v135, v121
	v_add_f32_e32 v121, v132, v121
	v_add_f32_e32 v121, v185, v121
	v_add_f32_e32 v121, v133, v121
	v_add_f32_e32 v121, v186, v121
	v_add_f32_e32 v121, v122, v121
	s_waitcnt lgkmcnt(8)
	v_mfma_f32_32x32x16_bf16 v[32:47], v[36:39], v[84:87], 0
	v_add_f32_e32 v121, v125, v121
	v_add_f32_e32 v121, v123, v121
	v_add_f32_e32 v121, v126, v121
	v_exp_f32_e32 v116, v116
	v_add_f32_e32 v121, v124, v121
	v_exp_f32_e32 v117, v117
	v_add_f32_e32 v121, v127, v121
	s_waitcnt lgkmcnt(7)
	v_mfma_f32_32x32x16_bf16 v[48:63], v[192:195], v[80:83], v[48:63]
	v_exp_f32_e32 v114, v114
	v_add_f32_e32 v121, v128, v121
	v_exp_f32_e32 v115, v115
	v_add_f32_e32 v121, v129, v121
	v_exp_f32_e32 v110, v110
	v_add_f32_e32 v121, v116, v121
	v_exp_f32_e32 v111, v111
	s_waitcnt lgkmcnt(6)
	v_mfma_f32_32x32x16_bf16 v[32:47], v[196:199], v[80:83], v[32:47]
	v_add_f32_e32 v121, v117, v121
	v_exp_f32_e32 v106, v106
	v_add_f32_e32 v121, v114, v121
	v_exp_f32_e32 v107, v107
	v_add_f32_e32 v121, v115, v121
	v_exp_f32_e32 v104, v104
	v_add_f32_e32 v121, v110, v121
	s_waitcnt lgkmcnt(5)
	v_mfma_f32_32x32x16_bf16 v[48:63], v[200:203], v[76:79], v[48:63]
	ds_read_b128 v[224:227], v180 offset:49152
	ds_read_b128 v[228:231], v180 offset:57344
	v_exp_f32_e32 v105, v105
	v_add_f32_e32 v121, v111, v121
	v_exp_f32_e32 v118, v118
	v_add_f32_e32 v121, v106, v121
	v_exp_f32_e32 v119, v119
	v_add_f32_e32 v121, v107, v121
	s_waitcnt lgkmcnt(6)
	v_mfma_f32_32x32x16_bf16 v[32:47], v[204:207], v[76:79], v[32:47]
	v_exp_f32_e32 v112, v112
	v_add_f32_e32 v121, v104, v121
	v_exp_f32_e32 v113, v113
	v_add_f32_e32 v121, v105, v121
	v_exp_f32_e32 v108, v108
	v_add_f32_e32 v121, v118, v121
	v_exp_f32_e32 v109, v109
	s_waitcnt lgkmcnt(5)
	v_mfma_f32_32x32x16_bf16 v[48:63], v[208:211], v[72:75], v[48:63]
	v_add_f32_e32 v121, v119, v121
	v_add_f32_e32 v121, v112, v121
	v_add_f32_e32 v121, v113, v121
	v_add_f32_e32 v121, v108, v121
	v_add_f32_e32 v182, v109, v121
	v_mov_b32_e32 v183, v182
	v_cvt_pk_bf16_f32 v130, v130, v134
	s_waitcnt lgkmcnt(4)
	v_mfma_f32_32x32x16_bf16 v[32:47], v[212:215], v[72:75], v[32:47]
	v_cvt_pk_bf16_f32 v131, v131, v135
	v_cvt_pk_bf16_f32 v132, v132, v185
	v_cvt_pk_bf16_f32 v133, v133, v186
	v_cvt_pk_bf16_f32 v122, v122, v125
	v_cvt_pk_bf16_f32 v123, v123, v126
	v_cvt_pk_bf16_f32 v124, v124, v127
	v_cvt_pk_bf16_f32 v125, v128, v129
	s_waitcnt lgkmcnt(3)
	v_mfma_f32_32x32x16_bf16 v[48:63], v[216:219], v[68:71], v[48:63]
	v_cvt_pk_bf16_f32 v126, v116, v117
	v_cvt_pk_bf16_f32 v127, v114, v115
	v_cvt_pk_bf16_f32 v128, v110, v111
	v_cvt_pk_bf16_f32 v129, v106, v107
	v_cvt_pk_bf16_f32 v184, v104, v105
	v_cvt_pk_bf16_f32 v185, v118, v119
	v_cvt_pk_bf16_f32 v186, v112, v113
	s_waitcnt lgkmcnt(2)
	v_mfma_f32_32x32x16_bf16 v[32:47], v[220:223], v[68:71], v[32:47]
	v_permlane32_swap_b32_e32 v182, v183
	v_cvt_pk_bf16_f32 v187, v108, v109
	v_permlane32_swap_b32_e32 v184, v186
	v_permlane32_swap_b32_e32 v130, v132
	s_waitcnt lgkmcnt(1)
	v_mfma_f32_32x32x16_bf16 v[48:63], v[224:227], v[64:67], v[48:63]
	v_permlane32_swap_b32_e32 v131, v133
	v_permlane32_swap_b32_e32 v122, v124
	v_permlane32_swap_b32_e32 v123, v125
	v_permlane32_swap_b32_e32 v126, v128
	s_waitcnt lgkmcnt(0)
	v_mfma_f32_32x32x16_bf16 v[32:47], v[228:231], v[64:67], v[32:47]
	v_permlane32_swap_b32_e32 v127, v129
	v_permlane32_swap_b32_e32 v185, v187
	v_add_co_u32_e32 v104, vcc, s48, v154
	v_lshl_add_u64 v[112:113], v[150:151], 0, v[160:161]
	s_nop 0
	v_addc_co_u32_e32 v105, vcc, -1, v155, vcc
	v_add_co_u32_e32 v108, vcc, s49, v154
	v_lshl_add_u64 v[116:117], v[150:151], 0, v[158:159]
	s_nop 0
	v_addc_co_u32_e32 v109, vcc, -1, v155, vcc
	global_load_dwordx4 v[104:107], v[104:105], off
	s_nop 0
	global_load_dwordx4 v[108:111], v[108:109], off
	s_nop 0
	global_load_dwordx4 v[112:115], v[112:113], off
	s_nop 0
	global_load_dwordx4 v[116:119], v[116:117], off
	s_waitcnt vmcnt(4)
	ds_write_b128 v171, v[88:91] offset:32768
	ds_write_b128 v172, v[92:95] offset:32768
	ds_read_b64_tr_b16 v[192:193], v170 offset:0
	ds_read_b64_tr_b16 v[194:195], v170 offset:0x800
	ds_read_b64_tr_b16 v[196:197], v170 offset:0x1000
	ds_read_b64_tr_b16 v[198:199], v170 offset:0x1800
	ds_read_b64_tr_b16 v[200:201], v170 offset:0x2000
	ds_read_b64_tr_b16 v[202:203], v170 offset:0x2800
	ds_read_b64_tr_b16 v[204:205], v170 offset:0x3000
	ds_read_b64_tr_b16 v[206:207], v170 offset:0x3800
	s_waitcnt lgkmcnt(6)
	v_mfma_f32_32x32x16_bf16 v[0:15], v[130:133], v[192:195], v[0:15]
	ds_read_b64_tr_b16 v[192:193], v170 offset:0x200
	ds_read_b64_tr_b16 v[194:195], v170 offset:0xa00
	v_max_f32_e32 v121, v49, v49
	v_max_f32_e32 v134, v48, v48
	v_max_f32_e32 v121, v134, v121
	v_max3_f32 v121, v121, v50, v51
	v_max3_f32 v121, v121, v52, v53
	v_max3_f32 v121, v121, v54, v55
	v_max3_f32 v121, v121, v56, v57
	v_max3_f32 v121, v121, v58, v59
	v_max3_f32 v121, v121, v60, v61
	v_max3_f32 v121, v121, v62, v63
	v_max3_f32 v121, v121, v32, v33
	v_max3_f32 v121, v121, v34, v35
	s_waitcnt lgkmcnt(6)
; #define SBAR() __builtin_amdgcn_sched_barrier(0)
; #define SWRITE(b, i) do { *(LAS bf16x8*)(V_lds + (b) * SHM_V + vst0) = sr_[i].vs0;          \
;     *(LAS bf16x8*)(V_lds + (b) * SHM_V + vst1) = sr_[i].vs1; const int kc = sc * 2;               \
;     *(LAS bf16x8*)(K_lds + (b) * SHM_K + KSWZ(sr, kc)) = sr_[i].ks0;                       \
;     *(LAS bf16x8*)(K_lds + (b) * SHM_K + KSWZ(32 + sr, kc)) = sr_[i].ks1; } while (0)
; #define SWAIT() asm volatile("s_waitcnt vmcnt(4)" ::: "memory")
; #define RESC(a) do { if (__any((a) < 1.f)) { if (hi == 0) al_l[r32] = (a); asm volatile("s_waitcnt lgkmcnt(0)" ::: "memory"); \
;     _Pragma("unroll") for (int d = 0; d < NDV; ++d) _Pragma("unroll") for (int r = 0; r < 16; ++r) o[d][r] *= al_l[crow(r, hi)]; } } while (0)
; template <int NDQ, int NDV> ...
;     ...
;     pv_d0<NDV>(o, vb0, pa0, pa1, pa2, pa3); partialSM(pB0, pB1, m_reg, mnB, alB, Cs, thr);
;     __syncthreads(); SWAIT(); SWRITE(0, SE);
;     RESC(alB); __syncthreads();
;     SBAR(); qkt<NDQ>(pA0, pA1, K_lds, qr, r32, hi);
;     finishSM(pB0, pB1, alB, l_reg, pa0, pa1, pa2, pa3); SBAR();
	v_mfma_f32_32x32x16_bf16 v[0:15], v[122:125], v[196:199], v[0:15]
	ds_read_b64_tr_b16 v[196:197], v170 offset:0x1200
	ds_read_b64_tr_b16 v[198:199], v170 offset:0x1a00
	v_max3_f32 v121, v121, v36, v37
	v_max3_f32 v121, v121, v38, v39
	v_max3_f32 v121, v121, v40, v41
	v_max3_f32 v121, v121, v42, v43
	v_max3_f32 v121, v121, v44, v45
	v_max3_f32 v121, v121, v46, v47
	v_mov_b32_e32 v134, v121
	s_nop 1
	v_permlane32_swap_b32_e32 v121, v134
	v_max_f32_e32 v134, v134, v134
	v_max_f32_e32 v121, v121, v121
	v_max_f32_e32 v121, v121, v134
	s_waitcnt lgkmcnt(6)
	v_mfma_f32_32x32x16_bf16 v[0:15], v[126:129], v[200:203], v[0:15]
	ds_read_b64_tr_b16 v[200:201], v170 offset:0x2200
	ds_read_b64_tr_b16 v[202:203], v170 offset:0x2a00
	ds_read_b64_tr_b16 v[208:209], v170 offset:0x3200
	ds_read_b64_tr_b16 v[210:211], v170 offset:0x3a00
	v_max_f32_e32 v252, v120, v120
	v_sub_f32_e32 v135, v121, v120
	v_max_f32_e32 v121, v252, v121
	v_sub_f32_e32 v252, v120, v121
	v_mul_f32_e32 v252, 0x3e16c740, v252
	v_exp_f32_e32 v252, v252
	v_cmp_ge_f32_e32 vcc, s46, v135
	s_cmp_eq_u64 vcc, exec
	s_cselect_b64 s[6:7], -1, 0
	v_cndmask_b32_e64 v253, v121, v120, s[6:7]
	v_mul_f32_e32 v251, 0xbe16c740, v253
	s_waitcnt lgkmcnt(8)
	v_mfma_f32_32x32x16_bf16 v[0:15], v[184:187], v[204:207], v[0:15]
	v_fmamk_f32 v48, v48, 0x3e16c740, v251
	v_fmamk_f32 v49, v49, 0x3e16c740, v251
	v_fmamk_f32 v50, v50, 0x3e16c740, v251
	v_fmamk_f32 v51, v51, 0x3e16c740, v251
	v_fmamk_f32 v52, v52, 0x3e16c740, v251
	v_fmamk_f32 v53, v53, 0x3e16c740, v251
	v_fmamk_f32 v54, v54, 0x3e16c740, v251
	v_fmamk_f32 v55, v55, 0x3e16c740, v251
	v_fmamk_f32 v56, v56, 0x3e16c740, v251
	v_fmamk_f32 v57, v57, 0x3e16c740, v251
	v_fmamk_f32 v58, v58, 0x3e16c740, v251
	v_fmamk_f32 v59, v59, 0x3e16c740, v251
	s_waitcnt lgkmcnt(6)
	v_mfma_f32_32x32x16_bf16 v[16:31], v[130:133], v[192:195], v[16:31]
	v_fmamk_f32 v60, v60, 0x3e16c740, v251
	v_fmamk_f32 v61, v61, 0x3e16c740, v251
	v_fmamk_f32 v62, v62, 0x3e16c740, v251
	v_fmamk_f32 v63, v63, 0x3e16c740, v251
	v_exp_f32_e32 v120, v48
	v_exp_f32_e32 v135, v49
	v_exp_f32_e32 v121, v50
	v_exp_f32_e32 v134, v51
	v_exp_f32_e32 v133, v53
	v_exp_f32_e32 v132, v55
	s_waitcnt lgkmcnt(4)
	v_mfma_f32_32x32x16_bf16 v[16:31], v[122:125], v[196:199], v[16:31]
	v_exp_f32_e32 v131, v57
	v_exp_f32_e32 v130, v59
	v_exp_f32_e32 v122, v52
	v_exp_f32_e32 v123, v54
	v_exp_f32_e32 v124, v56
	v_exp_f32_e32 v125, v58
	s_waitcnt lgkmcnt(2)
	v_mfma_f32_32x32x16_bf16 v[16:31], v[126:129], v[200:203], v[16:31]
	v_exp_f32_e32 v126, v60
	v_exp_f32_e32 v129, v61
	v_exp_f32_e32 v127, v62
	v_exp_f32_e32 v128, v63
	s_waitcnt lgkmcnt(0)
	v_mfma_f32_32x32x16_bf16 v[16:31], v[184:187], v[208:211], v[16:31]
	s_barrier
	s_waitcnt vmcnt(4)
	v_cndmask_b32_e64 v184, v252, 1.0, s[6:7]
	v_cmp_gt_f32_e32 vcc, 1.0, v184
	s_waitcnt vmcnt(4)
	ds_write_b128 v173, v[96:99]
	ds_write_b128 v174, v[100:103]
	s_cbranch_vccz .LBB0_1492
	s_and_saveexec_b64 s[10:11], s[4:5]
	ds_write_b32 v167, v184 offset:128
	s_or_b64 exec, exec, s[10:11]
	s_waitcnt lgkmcnt(0)
	v_add_u32_e32 v134, v149, v146
	ds_read_b128 v[122:125], v134 offset:224
	ds_read_b128 v[126:129], v134 offset:192
	ds_read_b128 v[130:133], v134 offset:160
	ds_read_b128 v[186:189], v134 offset:128
	s_waitcnt lgkmcnt(3)
	v_pk_mul_f32 v[12:13], v[12:13], v[122:123]
	s_waitcnt lgkmcnt(2)
	v_pk_mul_f32 v[8:9], v[8:9], v[126:127]
	s_waitcnt lgkmcnt(1)
	v_pk_mul_f32 v[4:5], v[4:5], v[130:131]
	v_pk_mul_f32 v[14:15], v[14:15], v[124:125]
	v_pk_mul_f32 v[10:11], v[10:11], v[128:129]
	v_pk_mul_f32 v[6:7], v[6:7], v[132:133]
	s_waitcnt lgkmcnt(0)
	v_pk_mul_f32 v[2:3], v[2:3], v[188:189]
	v_pk_mul_f32 v[0:1], v[0:1], v[186:187]
	v_pk_mul_f32 v[28:29], v[28:29], v[122:123]
	v_pk_mul_f32 v[24:25], v[24:25], v[126:127]
	v_pk_mul_f32 v[20:21], v[20:21], v[130:131]
	v_pk_mul_f32 v[30:31], v[30:31], v[124:125]
	v_pk_mul_f32 v[26:27], v[26:27], v[128:129]
	v_pk_mul_f32 v[22:23], v[22:23], v[132:133]
	v_pk_mul_f32 v[18:19], v[18:19], v[188:189]
	v_pk_mul_f32 v[16:17], v[16:17], v[186:187]
.LBB0_1492:
	v_mov_b32_e32 v185, v253
	v_fmamk_f32 v187, v38, 0x3e16c740, v251
	v_fmamk_f32 v188, v39, 0x3e16c740, v251
	v_fmamk_f32 v195, v32, 0x3e16c740, v251
	v_fmamk_f32 v196, v33, 0x3e16c740, v251
	v_fmamk_f32 v197, v34, 0x3e16c740, v251
	v_fmamk_f32 v198, v35, 0x3e16c740, v251
	v_fmamk_f32 v199, v36, 0x3e16c740, v251
	v_fmamk_f32 v200, v37, 0x3e16c740, v251
	v_fmamk_f32 v189, v40, 0x3e16c740, v251
	v_fmamk_f32 v191, v41, 0x3e16c740, v251
	v_fmamk_f32 v192, v42, 0x3e16c740, v251
	v_fmamk_f32 v193, v43, 0x3e16c740, v251
	v_fmamk_f32 v194, v44, 0x3e16c740, v251
	v_fmamk_f32 v201, v45, 0x3e16c740, v251
	v_fmamk_f32 v202, v46, 0x3e16c740, v251
	v_fmamk_f32 v186, v47, 0x3e16c740, v251
	ds_read_b128 v[32:35], v175 offset:32768
	ds_read_b128 v[36:39], v175 offset:40960
	ds_read_b128 v[204:207], v176 offset:32768
	ds_read_b128 v[208:211], v176 offset:40960
	ds_read_b128 v[212:215], v177 offset:32768
	ds_read_b128 v[216:219], v177 offset:40960
	ds_read_b128 v[220:223], v178 offset:32768
	ds_read_b128 v[224:227], v178 offset:40960
	ds_read_b128 v[228:231], v179 offset:32768
	ds_read_b128 v[232:235], v179 offset:40960
	v_exp_f32_e32 v203, v187
	v_add_f32_e32 v187, 0, v120
	s_waitcnt lgkmcnt(9)
	v_mfma_f32_32x32x16_bf16 v[48:63], v[32:35], v[84:87], 0
	v_add_f32_e32 v187, v135, v187
	v_add_f32_e32 v187, v121, v187
	v_add_f32_e32 v187, v134, v187
	v_add_f32_e32 v187, v122, v187
	v_add_f32_e32 v187, v133, v187
	v_add_f32_e32 v187, v123, v187
	v_add_f32_e32 v187, v132, v187
	s_waitcnt lgkmcnt(8)
; #define SBAR() __builtin_amdgcn_sched_barrier(0)
; #define SLOAD(i, k0) do { sr_[i].vs0 = *reinterpret_cast<const bf16x8*>(vptr + (size_t)((k0) + sr) * vstr); \
;     sr_[i].vs1 = *reinterpret_cast<const bf16x8*>(vptr + (size_t)((k0) + 32 + sr) * vstr); \
;     sr_[i].ks0 = *reinterpret_cast<const bf16x8*>(kptr + (size_t)((k0) + sr) * kstr); \
;     sr_[i].ks1 = *reinterpret_cast<const bf16x8*>(kptr + (size_t)((k0) + 32 + sr) * kstr); } while (0)
; template <int NDQ, int NDV> ...
;     ...
;     SBAR(); qkt<NDQ>(pA0, pA1, K_lds, qr, r32, hi);
;     finishSM(pB0, pB1, alB, l_reg, pa0, pa1, pa2, pa3); SBAR();
;     if (j + 3 < NT) SLOAD(SE, (j + 3) * 64); SBAR();
	v_mfma_f32_32x32x16_bf16 v[32:47], v[36:39], v[84:87], 0
	v_add_f32_e32 v187, v124, v187
	v_add_f32_e32 v187, v131, v187
	v_add_f32_e32 v187, v125, v187
	v_add_f32_e32 v187, v130, v187
	v_exp_f32_e32 v195, v195
	v_add_f32_e32 v187, v126, v187
	v_exp_f32_e32 v196, v196
	s_waitcnt lgkmcnt(7)
	v_mfma_f32_32x32x16_bf16 v[48:63], v[204:207], v[80:83], v[48:63]
	v_add_f32_e32 v187, v129, v187
	v_exp_f32_e32 v197, v197
	v_add_f32_e32 v187, v127, v187
	v_exp_f32_e32 v198, v198
	v_add_f32_e32 v187, v128, v187
	v_exp_f32_e32 v199, v199
	v_add_f32_e32 v187, v195, v187
	s_waitcnt lgkmcnt(6)
	v_mfma_f32_32x32x16_bf16 v[32:47], v[208:211], v[80:83], v[32:47]
	v_exp_f32_e32 v200, v200
	v_add_f32_e32 v187, v196, v187
	v_add_f32_e32 v187, v197, v187
	v_exp_f32_e32 v204, v188
	v_add_f32_e32 v187, v198, v187
	v_exp_f32_e32 v189, v189
	v_add_f32_e32 v187, v199, v187
	s_waitcnt lgkmcnt(5)
	v_mfma_f32_32x32x16_bf16 v[48:63], v[212:215], v[76:79], v[48:63]
	ds_read_b128 v[236:239], v180 offset:32768
	ds_read_b128 v[240:243], v180 offset:40960
	v_exp_f32_e32 v191, v191
	v_add_f32_e32 v187, v200, v187
	v_exp_f32_e32 v192, v192
	v_add_f32_e32 v187, v203, v187
	v_exp_f32_e32 v193, v193
	v_add_f32_e32 v187, v204, v187
	s_waitcnt lgkmcnt(6)
	v_mfma_f32_32x32x16_bf16 v[32:47], v[216:219], v[76:79], v[32:47]
	v_exp_f32_e32 v194, v194
	v_add_f32_e32 v187, v189, v187
	v_exp_f32_e32 v201, v201
	v_add_f32_e32 v187, v191, v187
	v_exp_f32_e32 v202, v202
	v_add_f32_e32 v187, v192, v187
	v_exp_f32_e32 v186, v186
	s_waitcnt lgkmcnt(5)
	v_mfma_f32_32x32x16_bf16 v[48:63], v[220:223], v[72:75], v[48:63]
	v_add_f32_e32 v187, v193, v187
	v_add_f32_e32 v187, v194, v187
	v_add_f32_e32 v187, v201, v187
	v_add_f32_e32 v187, v202, v187
	v_add_f32_e32 v187, v186, v187
	v_mov_b32_e32 v188, v187
	v_cvt_pk_bf16_f32 v120, v120, v135
	s_waitcnt lgkmcnt(4)
	v_mfma_f32_32x32x16_bf16 v[32:47], v[224:227], v[72:75], v[32:47]
	v_cvt_pk_bf16_f32 v121, v121, v134
	v_cvt_pk_bf16_f32 v122, v122, v133
	v_cvt_pk_bf16_f32 v123, v123, v132
	v_cvt_pk_bf16_f32 v124, v124, v131
	v_cvt_pk_bf16_f32 v125, v125, v130
	v_cvt_pk_bf16_f32 v126, v126, v129
	v_cvt_pk_bf16_f32 v127, v127, v128
	s_waitcnt lgkmcnt(3)
	v_mfma_f32_32x32x16_bf16 v[48:63], v[228:231], v[68:71], v[48:63]
	v_cvt_pk_bf16_f32 v132, v195, v196
	v_cvt_pk_bf16_f32 v133, v197, v198
	v_cvt_pk_bf16_f32 v134, v199, v200
	v_cvt_pk_bf16_f32 v135, v203, v204
	v_cvt_pk_bf16_f32 v128, v189, v191
	v_cvt_pk_bf16_f32 v129, v192, v193
	v_cvt_pk_bf16_f32 v130, v194, v201
	s_waitcnt lgkmcnt(2)
	v_mfma_f32_32x32x16_bf16 v[32:47], v[232:235], v[68:71], v[32:47]
	v_cvt_pk_bf16_f32 v131, v202, v186
	v_permlane32_swap_b32_e32 v187, v188
	v_permlane32_swap_b32_e32 v120, v122
	v_permlane32_swap_b32_e32 v121, v123
	s_waitcnt lgkmcnt(1)
	v_mfma_f32_32x32x16_bf16 v[48:63], v[236:239], v[64:67], v[48:63]
	v_permlane32_swap_b32_e32 v124, v126
	v_permlane32_swap_b32_e32 v125, v127
	v_permlane32_swap_b32_e32 v132, v134
	v_permlane32_swap_b32_e32 v133, v135
	s_waitcnt lgkmcnt(0)
	v_mfma_f32_32x32x16_bf16 v[32:47], v[240:243], v[64:67], v[32:47]
	v_permlane32_swap_b32_e32 v128, v130
	v_permlane32_swap_b32_e32 v129, v131
	s_cmp_ge_u32 s57, s56
	s_cselect_b64 s[10:11], -1, 0
	s_and_b64 vcc, exec, s[10:11]
	s_cbranch_vccnz .LBB0_1494
	v_add_co_u32_e32 v88, vcc, 0xffff0000, v154
	v_lshl_add_u64 v[92:93], v[150:151], 0, v[152:153]
	s_nop 0
	v_addc_co_u32_e32 v89, vcc, -1, v155, vcc
	global_load_dwordx4 v[96:99], v[88:89], off
	global_load_dwordx4 v[100:103], v[154:155], off
	v_lshl_add_u64 v[88:89], v[150:151], 0, v[156:157]
	global_load_dwordx4 v[88:91], v[88:89], off
	s_nop 0
	global_load_dwordx4 v[92:95], v[92:93], off
.LBB0_1494:
	s_waitcnt vmcnt(4)
	s_cmp_lg_u64 s[10:11], 0
	s_cbranch_scc0 .Lmla_nodrain2
	s_waitcnt vmcnt(0)
; #define SBAR() __builtin_amdgcn_sched_barrier(0)
; #define SLOAD(i, k0) do { sr_[i].vs0 = *reinterpret_cast<const bf16x8*>(vptr + (size_t)((k0) + sr) * vstr); \
;     sr_[i].vs1 = *reinterpret_cast<const bf16x8*>(vptr + (size_t)((k0) + 32 + sr) * vstr); \
;     sr_[i].ks0 = *reinterpret_cast<const bf16x8*>(kptr + (size_t)((k0) + sr) * kstr); \
;     sr_[i].ks1 = *reinterpret_cast<const bf16x8*>(kptr + (size_t)((k0) + 32 + sr) * kstr); } while (0)
; #define SWRITE(b, i) do { *(LAS bf16x8*)(V_lds + (b) * SHM_V + vst0) = sr_[i].vs0;          \
;     *(LAS bf16x8*)(V_lds + (b) * SHM_V + vst1) = sr_[i].vs1; const int kc = sc * 2;               \
;     *(LAS bf16x8*)(K_lds + (b) * SHM_K + KSWZ(sr, kc)) = sr_[i].ks0;                       \
;     *(LAS bf16x8*)(K_lds + (b) * SHM_K + KSWZ(32 + sr, kc)) = sr_[i].ks1; } while (0)
; #define SWAIT() asm volatile("s_waitcnt vmcnt(4)" ::: "memory")
; #define RESC(a) do { if (__any((a) < 1.f)) { if (hi == 0) al_l[r32] = (a); asm volatile("s_waitcnt lgkmcnt(0)" ::: "memory"); \
;     _Pragma("unroll") for (int d = 0; d < NDV; ++d) _Pragma("unroll") for (int r = 0; r < 16; ++r) o[d][r] *= al_l[crow(r, hi)]; } } while (0)
; template <int NDQ, int NDV> ...
;     ...
;     if (j + 3 < NT) SLOAD(SE, (j + 3) * 64); SBAR();
;     pv_d0<NDV>(o, vb0 + SHM_V, pa0, pa1, pa2, pa3); partialSM(pA0, pA1, m_reg, mnA, alA, Cs, thr);
;     __syncthreads(); SWAIT(); SWRITE(1, SO);
;     RESC(alA); __syncthreads();
.Lmla_nodrain2:
	ds_write_b128 v171, v[112:115] offset:49152
	ds_write_b128 v172, v[116:119] offset:49152
	ds_read_b64_tr_b16 v[192:193], v168 offset:0
	ds_read_b64_tr_b16 v[194:195], v168 offset:0x800
	ds_read_b64_tr_b16 v[196:197], v168 offset:0x1000
	ds_read_b64_tr_b16 v[198:199], v168 offset:0x1800
	ds_read_b64_tr_b16 v[200:201], v168 offset:0x2000
	ds_read_b64_tr_b16 v[202:203], v168 offset:0x2800
	ds_read_b64_tr_b16 v[204:205], v168 offset:0x3000
	ds_read_b64_tr_b16 v[206:207], v168 offset:0x3800
	s_waitcnt lgkmcnt(6)
	v_mfma_f32_32x32x16_bf16 v[0:15], v[120:123], v[192:195], v[0:15]
	ds_read_b64_tr_b16 v[192:193], v168 offset:0x200
	ds_read_b64_tr_b16 v[194:195], v168 offset:0xa00
	v_max_f32_e32 v186, v49, v49
	v_max_f32_e32 v189, v48, v48
	v_max_f32_e32 v186, v189, v186
	v_max3_f32 v186, v186, v50, v51
	v_max3_f32 v186, v186, v52, v53
	v_max3_f32 v186, v186, v54, v55
	v_max3_f32 v186, v186, v56, v57
	v_max3_f32 v186, v186, v58, v59
	v_max3_f32 v186, v186, v60, v61
	v_max3_f32 v186, v186, v62, v63
	v_max3_f32 v186, v186, v32, v33
	v_max3_f32 v186, v186, v34, v35
	s_waitcnt lgkmcnt(6)
	v_mfma_f32_32x32x16_bf16 v[0:15], v[124:127], v[196:199], v[0:15]
	ds_read_b64_tr_b16 v[196:197], v168 offset:0x1200
	ds_read_b64_tr_b16 v[198:199], v168 offset:0x1a00
	v_max3_f32 v186, v186, v36, v37
	v_max3_f32 v186, v186, v38, v39
	v_max3_f32 v186, v186, v40, v41
	v_max3_f32 v186, v186, v42, v43
	v_max3_f32 v186, v186, v44, v45
	v_max3_f32 v186, v186, v46, v47
	v_mov_b32_e32 v189, v186
	s_nop 1
	v_permlane32_swap_b32_e32 v186, v189
	v_max_f32_e32 v189, v189, v189
	v_max_f32_e32 v186, v186, v186
	v_max_f32_e32 v186, v186, v189
	s_waitcnt lgkmcnt(6)
	v_mfma_f32_32x32x16_bf16 v[0:15], v[132:135], v[200:203], v[0:15]
	ds_read_b64_tr_b16 v[200:201], v168 offset:0x2200
	ds_read_b64_tr_b16 v[202:203], v168 offset:0x2a00
	ds_read_b64_tr_b16 v[208:209], v168 offset:0x3200
	ds_read_b64_tr_b16 v[210:211], v168 offset:0x3a00
	v_max_f32_e32 v252, v185, v185
	v_sub_f32_e32 v189, v186, v185
	v_max_f32_e32 v186, v252, v186
	v_sub_f32_e32 v252, v185, v186
	v_mul_f32_e32 v252, 0x3e16c740, v252
	v_exp_f32_e32 v252, v252
	v_cmp_ge_f32_e32 vcc, s46, v189
	s_cmp_eq_u64 vcc, exec
	s_cselect_b64 s[6:7], -1, 0
	v_cndmask_b32_e64 v253, v186, v185, s[6:7]
	v_mul_f32_e32 v250, 0xbe16c740, v253
	s_waitcnt lgkmcnt(8)
	v_mfma_f32_32x32x16_bf16 v[0:15], v[128:131], v[204:207], v[0:15]
	v_fmamk_f32 v48, v48, 0x3e16c740, v250
	v_fmamk_f32 v49, v49, 0x3e16c740, v250
	v_fmamk_f32 v50, v50, 0x3e16c740, v250
	v_fmamk_f32 v51, v51, 0x3e16c740, v250
	v_fmamk_f32 v52, v52, 0x3e16c740, v250
	v_fmamk_f32 v53, v53, 0x3e16c740, v250
	v_fmamk_f32 v54, v54, 0x3e16c740, v250
	v_fmamk_f32 v55, v55, 0x3e16c740, v250
	v_fmamk_f32 v56, v56, 0x3e16c740, v250
	v_fmamk_f32 v57, v57, 0x3e16c740, v250
	v_fmamk_f32 v58, v58, 0x3e16c740, v250
	v_fmamk_f32 v59, v59, 0x3e16c740, v250
	s_waitcnt lgkmcnt(6)
	v_mfma_f32_32x32x16_bf16 v[16:31], v[120:123], v[192:195], v[16:31]
	v_fmamk_f32 v60, v60, 0x3e16c740, v250
	v_fmamk_f32 v61, v61, 0x3e16c740, v250
	v_fmamk_f32 v62, v62, 0x3e16c740, v250
	v_fmamk_f32 v63, v63, 0x3e16c740, v250
	v_exp_f32_e32 v185, v53
	v_exp_f32_e32 v186, v55
	v_exp_f32_e32 v122, v56
	v_exp_f32_e32 v123, v58
	s_waitcnt lgkmcnt(4)
	v_mfma_f32_32x32x16_bf16 v[16:31], v[124:127], v[196:199], v[16:31]
	v_exp_f32_e32 v124, v60
	v_exp_f32_e32 v125, v57
	v_exp_f32_e32 v126, v59
	v_exp_f32_e32 v127, v61
	s_waitcnt lgkmcnt(2)
	v_mfma_f32_32x32x16_bf16 v[16:31], v[132:135], v[200:203], v[16:31]
	v_exp_f32_e32 v132, v52
	v_exp_f32_e32 v133, v54
	v_exp_f32_e32 v134, v49
	v_exp_f32_e32 v135, v51
	s_waitcnt lgkmcnt(0)
	v_mfma_f32_32x32x16_bf16 v[16:31], v[128:131], v[208:211], v[16:31]
	v_exp_f32_e32 v128, v62
	v_exp_f32_e32 v129, v63
	v_exp_f32_e32 v130, v48
	v_exp_f32_e32 v131, v50
	s_barrier
	s_waitcnt vmcnt(4)
	s_cmp_lg_u64 s[10:11], 0
	s_cbranch_scc0 .Lmla_nodrain
	s_waitcnt vmcnt(0)
.Lmla_nodrain:
	v_cndmask_b32_e64 v121, v252, 1.0, s[6:7]
	v_cmp_gt_f32_e32 vcc, 1.0, v121
	ds_write_b128 v173, v[104:107] offset:16384
	ds_write_b128 v174, v[108:111] offset:16384
	s_cbranch_vccz .LBB0_1498
	s_and_saveexec_b64 s[12:13], s[4:5]
	ds_write_b32 v167, v121 offset:128
	s_or_b64 exec, exec, s[12:13]
	s_waitcnt lgkmcnt(0)
	v_add_u32_e32 v116, v149, v146
	ds_read_b128 v[104:107], v116 offset:224
	ds_read_b128 v[108:111], v116 offset:192
	ds_read_b128 v[112:115], v116 offset:160
	ds_read_b128 v[116:119], v116 offset:128
	s_waitcnt lgkmcnt(3)
	v_pk_mul_f32 v[12:13], v[12:13], v[104:105]
	s_waitcnt lgkmcnt(2)
	v_pk_mul_f32 v[8:9], v[8:9], v[108:109]
	s_waitcnt lgkmcnt(1)
	v_pk_mul_f32 v[4:5], v[4:5], v[112:113]
	v_pk_mul_f32 v[14:15], v[14:15], v[106:107]
	v_pk_mul_f32 v[10:11], v[10:11], v[110:111]
	v_pk_mul_f32 v[6:7], v[6:7], v[114:115]
	s_waitcnt lgkmcnt(0)
	v_pk_mul_f32 v[2:3], v[2:3], v[118:119]
	v_pk_mul_f32 v[0:1], v[0:1], v[116:117]
	v_pk_mul_f32 v[28:29], v[28:29], v[104:105]
	v_pk_mul_f32 v[24:25], v[24:25], v[108:109]
	v_pk_mul_f32 v[20:21], v[20:21], v[112:113]
	v_pk_mul_f32 v[30:31], v[30:31], v[106:107]
	v_pk_mul_f32 v[26:27], v[26:27], v[110:111]
	v_pk_mul_f32 v[22:23], v[22:23], v[114:115]
	v_pk_mul_f32 v[18:19], v[18:19], v[118:119]
	v_pk_mul_f32 v[16:17], v[16:17], v[116:117]
.LBB0_1498:
	v_mov_b32_e32 v120, v253
	v_pk_fma_f32 v[116:117], v[32:33], s[26:27], v[250:251] op_sel_hi:[1,0,0]
	v_add_f32_e32 v32, v182, v183
	v_fmac_f32_e32 v32, v181, v169
	v_add_f32_e32 v169, v187, v188
	v_pk_fma_f32 v[114:115], v[34:35], s[26:27], v[250:251] op_sel_hi:[1,0,0]
	v_pk_fma_f32 v[110:111], v[36:37], s[26:27], v[250:251] op_sel_hi:[1,0,0]
	v_pk_fma_f32 v[106:107], v[38:39], s[26:27], v[250:251] op_sel_hi:[1,0,0]
	v_pk_fma_f32 v[104:105], v[40:41], s[26:27], v[250:251] op_sel_hi:[1,0,0]
	v_pk_fma_f32 v[118:119], v[42:43], s[26:27], v[250:251] op_sel_hi:[1,0,0]
	v_pk_fma_f32 v[112:113], v[44:45], s[26:27], v[250:251] op_sel_hi:[1,0,0]
	v_pk_fma_f32 v[108:109], v[46:47], s[26:27], v[250:251] op_sel_hi:[1,0,0]
	v_fmac_f32_e32 v169, v32, v184
	v_lshl_add_u64 v[150:151], v[150:151], 0, v[136:137]
	v_lshl_add_u64 v[154:155], v[154:155], 0, s[28:29]
	s_add_i32 s57, s57, 2
	s_and_b64 vcc, exec, s[10:11]
	s_cbranch_vccnz .LBB0_1500
	v_mov_b32_e32 v181, v121
	s_branch .LBB0_1488
